# all 10 compiler grid-barrier instances replaced by a lean hand-written XCD barrier (static generation numbers, one cumulative top counter, release before acquire)
# speedup vs baseline: 1.0088x; 1.0088x over previous
.Lgb0_census_ok:
	v_cmp_ne_u32_e32 vcc, 0, v254
	s_nop 1
	s_bcnt1_i32_b64 s9, vcc
	v_readlane_b32 s8, v254, s7
	s_nop 1
	s_max_u32 s8, s8, 1
	s_max_u32 s9, s9, 1
	s_mov_b64 exec, 1
	v_writelane_b32 v249, s8, 14
	v_writelane_b32 v249, s9, 15
	v_mov_b32_e32 v253, 0x23f00
	v_mov_b32_e32 v254, s8
	v_mov_b32_e32 v255, s9
	ds_write2_b32 v253, v254, v255 offset1:1
	s_cmp_lg_u32 s96, 0
	s_cbranch_scc1 .Lgb0_noclr
	s_add_u32 s10, s4, 0x10000
	s_addc_u32 s11, s5, 0
	v_mov_b32_e32 v2, 0
	v_mov_b32_e32 v3, 0
	global_store_dwordx2 v250, v[2:3], s[10:11] sc1
.Lgb0_noclr:
	v_add_u32_e32 v253, 0x1000, v251
	v_add_u32_e32 v255, 0x2000, v251
	s_nop 0
	global_atomic_add v254, v253, v252, s[4:5] offset:1024 sc0
	s_waitcnt vmcnt(0)
	v_readfirstlane_b32 s10, v254
	s_nop 1
	s_add_u32 s10, s10, 1
	s_cmp_eq_u32 s10, s8
	s_cbranch_scc0 .Lgb0_follower
	buffer_wbl2 sc1
	s_waitcnt vmcnt(0)
	global_atomic_add v254, v0, v252, s[4:5] sc0
	s_waitcnt vmcnt(0)
	v_readfirstlane_b32 s10, v254
	s_nop 1
	s_add_u32 s10, s10, 1
	s_cmp_eq_u32 s10, s9
	s_cbranch_scc0 .Lgb0_topwait
	global_atomic_add v0, v252, s[4:5] offset:256
	s_branch .Lgb0_topdone

.LBB0_127:
	s_waitcnt vmcnt(0)
	s_barrier
	s_mov_b64 s[2:3], exec
	v_readlane_b32 s4, v248, 7
	v_readlane_b32 s5, v248, 8
	s_and_b64 s[4:5], s[2:3], s[4:5]
	s_mov_b64 exec, s[4:5]
	s_cbranch_execz .LBB0_179
	v_readlane_b32 s4, v248, 4
	v_readlane_b32 s5, v248, 5
	v_readlane_b32 s8, v248, 6
	v_readlane_b32 s9, v249, 14
	v_readlane_b32 s10, v249, 15
	v_mov_b32_e32 v1, 1
	v_mov_b32_e32 v3, 0x3400
	s_nop 1
	s_lshl_b32 s8, s8, 8
	s_mul_i32 s9, s9, 2
	s_mul_i32 s10, s10, 2
	v_mov_b32_e32 v0, s8
	v_add_u32_e32 v2, 0x1000, v0
	v_add_u32_e32 v4, 0x2000, v0
	s_nop 1
	global_atomic_add v5, v2, v1, s[4:5] offset:1024 sc0
	s_waitcnt vmcnt(0)
	v_readfirstlane_b32 s11, v5
	s_nop 1
	s_add_u32 s11, s11, 1
	s_cmp_eq_u32 s11, s9
	s_cbranch_scc0 .Lhb1_follower
	buffer_wbl2 sc1
	s_waitcnt vmcnt(0)
	global_atomic_add v5, v3, v1, s[4:5] sc0
	s_waitcnt vmcnt(0)
	v_readfirstlane_b32 s11, v5
	s_nop 1
	s_add_u32 s11, s11, 1
	s_cmp_ge_u32 s11, s10
	s_cbranch_scc1 .Lhb1_topdone
	s_movk_i32 s12, 0x4000
.Lhb1_topspin:
	global_load_dword v5, v3, s[4:5] sc1
	s_waitcnt vmcnt(0)
	v_readfirstlane_b32 s11, v5
	s_nop 1
	s_cmp_ge_u32 s11, s10
	s_cbranch_scc1 .Lhb1_topdone
	s_sleep 1
	s_sub_u32 s12, s12, 1
	s_cmp_lg_u32 s12, 0
	s_cbranch_scc1 .Lhb1_topspin
.Lhb1_topdone:
	global_atomic_add v4, v1, s[4:5] offset:1024
	buffer_inv sc1
	s_waitcnt vmcnt(0)
	s_branch .Lhb1_done
.Lhb1_follower:
	s_movk_i32 s12, 0x4000
.Lhb1_fspin:
	global_load_dword v5, v4, s[4:5] offset:1024 sc1
	s_waitcnt vmcnt(0)
	v_readfirstlane_b32 s11, v5
	s_nop 1
	s_cmp_gt_u32 s11, 1
	s_cbranch_scc1 .Lhb1_fdone
	s_sleep 1
	s_sub_u32 s12, s12, 1
	s_cmp_lg_u32 s12, 0
	s_cbranch_scc1 .Lhb1_fspin

.Lhb1_done:
.LBB0_179:
	s_or_b64 exec, exec, s[2:3]
	s_waitcnt lgkmcnt(0)
	v_mov_b32_e32 v0, v192
	v_mov_b32_e32 v8, v192
	s_cmpk_lt_i32 s96, 0x6b4
	s_barrier
	s_cselect_b64 s[2:3], -1, 0
	s_cmpk_gt_i32 s96, 0x6b3
	v_readfirstlane_b32 s6, v8
	s_cbranch_scc1 .LBB0_185
	s_ashr_i32 s4, s96, 31
	s_lshr_b32 s4, s4, 29
	s_add_i32 s7, s96, s4
	s_and_b32 s4, s7, -8
	s_sub_i32 s8, s96, s4
	s_cmp_gt_i32 s8, 3
	s_cbranch_scc0 .LBB0_182
	s_mul_i32 s4, s8, 0xd6
	s_add_i32 s9, s4, 4
	s_cbranch_execz .LBB0_183
	s_branch .LBB0_184

.LBB0_309:
	s_waitcnt vmcnt(0)
	s_barrier
	s_mov_b64 s[2:3], exec
	v_readlane_b32 s4, v248, 7
	v_readlane_b32 s5, v248, 8
	s_and_b64 s[4:5], s[2:3], s[4:5]
	s_mov_b64 exec, s[4:5]
	s_cbranch_execz .LBB0_361
	v_readlane_b32 s4, v248, 4
	v_readlane_b32 s5, v248, 5
	v_readlane_b32 s8, v248, 6
	v_readlane_b32 s9, v249, 14
	v_readlane_b32 s10, v249, 15
	v_mov_b32_e32 v1, 1
	v_mov_b32_e32 v3, 0x3400
	s_nop 1
	s_lshl_b32 s8, s8, 8
	s_mul_i32 s9, s9, 3
	s_mul_i32 s10, s10, 3
	v_mov_b32_e32 v0, s8
	v_add_u32_e32 v2, 0x1000, v0
	v_add_u32_e32 v4, 0x2000, v0
	s_nop 1
	global_atomic_add v5, v2, v1, s[4:5] offset:1024 sc0
	s_waitcnt vmcnt(0)
	v_readfirstlane_b32 s11, v5
	s_nop 1
	s_add_u32 s11, s11, 1
	s_cmp_eq_u32 s11, s9
	s_cbranch_scc0 .Lhb2_follower
	buffer_wbl2 sc1
	s_waitcnt vmcnt(0)
	global_atomic_add v5, v3, v1, s[4:5] sc0
	s_waitcnt vmcnt(0)
	v_readfirstlane_b32 s11, v5
	s_nop 1
	s_add_u32 s11, s11, 1
	s_cmp_ge_u32 s11, s10
	s_cbranch_scc1 .Lhb2_topdone
	s_movk_i32 s12, 0x4000

.Lhb2_fspin:
	global_load_dword v5, v4, s[4:5] offset:1024 sc1
	s_waitcnt vmcnt(0)
	v_readfirstlane_b32 s11, v5
	s_nop 1
	s_cmp_gt_u32 s11, 2
	s_cbranch_scc1 .Lhb2_fdone
	s_sleep 1
	s_sub_u32 s12, s12, 1
	s_cmp_lg_u32 s12, 0
	s_cbranch_scc1 .Lhb2_fspin

.Lhb2_done:
.LBB0_361:
	s_or_b64 exec, exec, s[2:3]
	v_mov_b32_e32 v96, v192
	s_waitcnt lgkmcnt(0)
	s_barrier
	s_load_dwordx2 s[68:69], s[0:1], 0xf0
	v_readlane_b32 s2, v248, 1
	v_readfirstlane_b32 s51, v96
	s_waitcnt lgkmcnt(0)
	s_add_u32 s62, s68, 0x8b00000
	v_add_u32_e32 v6, s2, v96
	s_mov_b32 s2, 0x20000
	s_addc_u32 s63, s69, 0
	v_cmp_gt_i32_e32 vcc, s2, v6
	s_and_saveexec_b64 s[2:3], vcc
	s_cbranch_execz .LBB0_368
	v_and_b32_e32 v4, 0x1ff, v96
	s_movk_i32 s4, 0xff
	v_cmp_lt_u32_e64 s[6:7], s4, v4
	s_load_dwordx2 s[4:5], s[0:1], 0xe8
	v_mov_b32_e32 v1, 0
	v_lshlrev_b32_e32 v0, 1, v4
	s_lshl_b32 s12, s92, 9
	v_lshl_add_u64 v[2:3], s[62:63], 0, v[0:1]
	s_mov_b64 s[8:9], 0
	s_movk_i32 s13, 0x1f80
	s_mov_b32 s14, 0x1ffff
	v_lshlrev_b32_e32 v0, 2, v4
	s_branch .LBB0_364

.LBB0_616:
	s_waitcnt vmcnt(0)
	s_barrier
	s_mov_b64 s[2:3], exec
	v_readlane_b32 s4, v248, 7
	v_readlane_b32 s5, v248, 8
	s_and_b64 s[4:5], s[2:3], s[4:5]
	s_mov_b64 exec, s[4:5]
	s_cbranch_execz .LBB0_668
	v_readlane_b32 s4, v248, 4
	v_readlane_b32 s5, v248, 5
	v_readlane_b32 s8, v248, 6
	v_readlane_b32 s9, v249, 14
	v_readlane_b32 s10, v249, 15
	v_mov_b32_e32 v1, 1
	v_mov_b32_e32 v3, 0x3400
	s_nop 1
	s_lshl_b32 s8, s8, 8
	s_mul_i32 s9, s9, 4
	s_mul_i32 s10, s10, 4
	v_mov_b32_e32 v0, s8
	v_add_u32_e32 v2, 0x1000, v0
	v_add_u32_e32 v4, 0x2000, v0
	s_nop 1
	global_atomic_add v5, v2, v1, s[4:5] offset:1024 sc0
	s_waitcnt vmcnt(0)
	v_readfirstlane_b32 s11, v5
	s_nop 1
	s_add_u32 s11, s11, 1
	s_cmp_eq_u32 s11, s9
	s_cbranch_scc0 .Lhb3_follower
	buffer_wbl2 sc1
	s_waitcnt vmcnt(0)
	global_atomic_add v5, v3, v1, s[4:5] sc0
	s_waitcnt vmcnt(0)
	v_readfirstlane_b32 s11, v5
	s_nop 1
	s_add_u32 s11, s11, 1
	s_cmp_ge_u32 s11, s10
	s_cbranch_scc1 .Lhb3_topdone
	s_movk_i32 s12, 0x4000

.Lhb3_fspin:
	global_load_dword v5, v4, s[4:5] offset:1024 sc1
	s_waitcnt vmcnt(0)
	v_readfirstlane_b32 s11, v5
	s_nop 1
	s_cmp_gt_u32 s11, 3
	s_cbranch_scc1 .Lhb3_fdone
	s_sleep 1
	s_sub_u32 s12, s12, 1
	s_cmp_lg_u32 s12, 0
	s_cbranch_scc1 .Lhb3_fspin

.Lhb3_done:
.LBB0_668:
	s_or_b64 exec, exec, s[2:3]
	s_cmpk_lt_i32 s96, 0x100
	s_cselect_b64 s[2:3], -1, 0
	v_mov_b32_e32 v4, v192
	v_writelane_b32 v248, s2, 35
	s_cmpk_gt_i32 s96, 0xff
	s_waitcnt lgkmcnt(0)
	s_barrier
	v_writelane_b32 v248, s3, 36
	s_cbranch_scc1 .LBB0_686
	s_load_dwordx4 s[16:19], s[0:1], 0xe8
	s_movk_i32 s2, 0x80
	v_cmp_gt_i32_e64 s[12:13], s2, v4
	v_ashrrev_i32_e32 v5, 31, v4
	v_lshlrev_b32_e32 v2, 3, v4
	s_waitcnt lgkmcnt(0)
	s_add_u32 s2, s18, 0x2750000
	s_addc_u32 s3, s19, 0
	s_add_u32 s4, s18, 0x2751000
	s_addc_u32 s5, s19, 0
	s_add_u32 s6, s16, 0x4200000
	v_lshl_add_u64 v[0:1], v[4:5], 2, s[18:19]
	s_mov_b64 s[18:19], 0x2754000
	v_cmp_eq_u32_e64 s[8:9], 0, v4
	v_cmp_gt_i32_e64 s[10:11], 64, v4
	s_addc_u32 s7, s17, 0
	v_cmp_eq_u32_e64 s[14:15], 64, v4
	v_lshlrev_b32_e32 v134, 1, v4
	v_lshl_add_u32 v135, v4, 2, 0
	v_lshl_add_u64 v[6:7], v[0:1], 0, s[18:19]
	v_mov_b32_e32 v0, 0
	v_add_u32_e32 v136, 0, v2
	v_mov_b32_e32 v137, 0x4301000
	s_mov_b32 s24, 0x10000
	s_mov_b32 s25, 0x20000
	s_mov_b32 s26, 0x30000
	s_mov_b32 s27, 0x40000
	s_mov_b32 s28, 0x50000
	s_mov_b32 s29, 0x60000
	s_mov_b32 s30, 0x70000
	s_mov_b32 s31, 0x80000
	s_mov_b32 s33, 0x90000
	s_mov_b32 s34, 0xa0000
	s_mov_b32 s35, 0xb0000
	s_mov_b32 s36, 0xc0000
	s_mov_b32 s37, 0xd0000
	s_mov_b32 s38, 0xe0000
	s_mov_b32 s39, 0xf0000
	s_mov_b32 s40, s96
	s_mov_b32 s41, s96
	s_branch .LBB0_671

.LBB0_686:
	s_waitcnt vmcnt(0)
	s_waitcnt vmcnt(63) expcnt(7) lgkmcnt(15)
	s_barrier
	s_mov_b64 s[2:3], exec
	v_readlane_b32 s4, v248, 7
	v_readlane_b32 s5, v248, 8
	s_and_b64 s[4:5], s[2:3], s[4:5]
	s_mov_b64 exec, s[4:5]
	s_cbranch_execz .LBB0_738
	v_readlane_b32 s4, v248, 4
	v_readlane_b32 s5, v248, 5
	v_readlane_b32 s8, v248, 6
	v_readlane_b32 s9, v249, 14
	v_readlane_b32 s10, v249, 15
	v_mov_b32_e32 v1, 1
	v_mov_b32_e32 v3, 0x3400
	s_nop 1
	s_lshl_b32 s8, s8, 8
	s_mul_i32 s9, s9, 5
	s_mul_i32 s10, s10, 5
	v_mov_b32_e32 v0, s8
	v_add_u32_e32 v2, 0x1000, v0
	v_add_u32_e32 v4, 0x2000, v0
	s_nop 1
	global_atomic_add v5, v2, v1, s[4:5] offset:1024 sc0
	s_waitcnt vmcnt(0)
	v_readfirstlane_b32 s11, v5
	s_nop 1
	s_add_u32 s11, s11, 1
	s_cmp_eq_u32 s11, s9
	s_cbranch_scc0 .Lhb4_follower
	buffer_wbl2 sc1
	s_waitcnt vmcnt(0)
	global_atomic_add v5, v3, v1, s[4:5] sc0
	s_waitcnt vmcnt(0)
	v_readfirstlane_b32 s11, v5
	s_nop 1
	s_add_u32 s11, s11, 1
	s_cmp_ge_u32 s11, s10
	s_cbranch_scc1 .Lhb4_topdone
	s_movk_i32 s12, 0x4000

.Lhb4_fspin:
	global_load_dword v5, v4, s[4:5] offset:1024 sc1
	s_waitcnt vmcnt(0)
	v_readfirstlane_b32 s11, v5
	s_nop 1
	s_cmp_gt_u32 s11, 4
	s_cbranch_scc1 .Lhb4_fdone
	s_sleep 1
	s_sub_u32 s12, s12, 1
	s_cmp_lg_u32 s12, 0
	s_cbranch_scc1 .Lhb4_fspin

.Lhb4_done:
.LBB0_738:
	s_or_b64 exec, exec, s[2:3]
	v_mov_b32_e32 v2, v192
	s_waitcnt lgkmcnt(0)
	s_barrier
	s_and_b64 vcc, exec, s[84:85]
	v_readfirstlane_b32 s10, v2
	s_cbranch_vccnz .LBB0_819
	s_load_dwordx4 s[88:91], s[0:1], 0xe8
	s_ashr_i32 s2, s10, 6
	v_lshlrev_b32_e32 v0, 4, v2
	v_and_b32_e32 v68, 0xf0, v0
	v_mov_b32_e32 v69, 0
	s_waitcnt lgkmcnt(0)
	s_add_u32 s4, s90, 0x4900000
	s_addc_u32 s5, s91, 0
	v_lshl_add_u64 v[0:1], s[90:91], 0, v[68:69]
	s_mov_b64 s[6:7], 0x2800000
	s_cmp_lt_u32 s10, 64
	v_lshl_add_u64 v[70:71], v[0:1], 0, s[6:7]
	s_cselect_b64 s[6:7], -1, 0
	v_writelane_b32 v248, s6, 13
	v_and_b32_e32 v3, 63, v2
	v_cmp_gt_u32_e64 s[8:9], 2, v3
	v_writelane_b32 v248, s7, 14
	s_add_u32 s6, s90, 0x26a0000
	s_addc_u32 s7, s91, 0
	v_writelane_b32 v248, s6, 29
	v_lshlrev_b32_e32 v0, 3, v3
	s_add_i32 s3, 0, 0x22200
	v_writelane_b32 v248, s7, 30
	v_writelane_b32 v248, s8, 18
	v_add_u32_e32 v103, s3, v0
	s_add_i32 s3, 0, 0x22400
	v_writelane_b32 v248, s9, 19
	v_cmp_gt_u32_e64 s[8:9], 4, v3
	v_add_u32_e32 v104, s3, v0
	s_add_i32 s3, 0, 0x22600
	v_writelane_b32 v248, s8, 20
	v_add_u32_e32 v105, s3, v0
	s_add_i32 s3, 0, 0x22800
	v_writelane_b32 v248, s9, 21
	v_cmp_gt_u32_e64 s[8:9], 8, v3
	s_add_i32 s11, 0, 0x22000
	v_add_u32_e32 v106, s3, v0
	v_writelane_b32 v248, s8, 31
	s_movk_i32 s3, 0x80
	v_lshlrev_b32_e32 v101, 1, v3
	v_writelane_b32 v248, s9, 32
	v_cmp_gt_u32_e64 s[8:9], 16, v3
	v_cmp_eq_u32_e64 s[6:7], 0, v3
	v_cmp_gt_u32_e64 s[16:17], 32, v3
	v_writelane_b32 v248, s8, 33
	v_cmp_gt_i32_e64 s[12:13], s3, v2
	s_add_u32 s3, s90, 0x2751000
	v_writelane_b32 v248, s9, 34
	v_ashrrev_i32_e32 v3, 31, v2
	v_add_u32_e32 v17, 0x200, v2
	s_waitcnt vmcnt(0)
	v_add_u32_e32 v18, 0x400, v2
	v_add_u32_e32 v19, 0x600, v2
	v_add_u32_e32 v102, s11, v0
	v_writelane_b32 v248, s3, 15
	s_addc_u32 s3, s91, 0
	v_lshl_add_u64 v[0:1], v[2:3], 2, s[90:91]
	s_mov_b64 s[8:9], 0x2754000
	v_ashrrev_i32_e32 v95, 4, v2
	v_ashrrev_i32_e32 v98, 4, v17
	v_ashrrev_i32_e32 v99, 4, v18
	v_ashrrev_i32_e32 v100, 4, v19
	v_writelane_b32 v248, s3, 16
	v_lshl_add_u64 v[90:91], v[0:1], 0, s[8:9]
	s_movk_i32 s3, 0x110
	s_and_b32 s20, s2, 3
	s_ashr_i32 s8, s10, 8
	v_lshl_add_u64 v[72:73], s[88:89], 0, v[68:69]
	s_add_i32 s14, 0, 0x22a00
	s_add_i32 s15, 0, 0x22c00
	s_add_i32 s18, 0, 0x22e00
	s_add_i32 s19, 0, 0x23200
	v_add_u32_e32 v0, 0, v68
	v_mul_lo_u32 v112, v95, s3
	v_mul_lo_u32 v114, v98, s3
	v_mul_lo_u32 v116, v99, s3
	v_mul_lo_u32 v118, v100, s3
	s_add_i32 s88, 0, 0x11000
	v_add_u32_e32 v20, 0x800, v2
	s_lshl_b32 s9, s8, 1
	s_lshl_b32 s21, s20, 5
	v_lshlrev_b32_e32 v4, 2, v2
	v_add_u32_e32 v113, v0, v112
	v_add_u32_e32 v115, v0, v114
	v_add_u32_e32 v117, v0, v116
	v_add_u32_e32 v119, v0, v118
	v_lshrrev_b32_e32 v0, 4, v20
	v_add_u32_e32 v21, 0xa00, v2
	s_cmp_ge_i32 s9, s20
	v_add_u32_e32 v107, s11, v4
	v_add_u32_e32 v108, s14, v4
	v_add_u32_e32 v109, s15, v4
	v_add_u32_e32 v110, s18, v4
	v_add_u32_e32 v111, s19, v4
	v_mul_lo_u32 v4, v0, s3
	v_lshrrev_b32_e32 v0, 4, v21
	v_add_u32_e32 v22, 0xc00, v2
	s_cselect_b64 s[22:23], -1, 0
	v_mul_lo_u32 v5, v0, s3
	v_lshrrev_b32_e32 v0, 4, v22
	v_add_u32_e32 v23, 0xe00, v2
	v_writelane_b32 v248, s22, 22
	v_mul_lo_u32 v6, v0, s3
	v_lshrrev_b32_e32 v0, 4, v23
	v_writelane_b32 v248, s23, 23
	s_or_b32 s22, s9, 1
	v_mul_lo_u32 v7, v0, s3
	v_and_b32_e32 v8, 31, v2
	v_bfe_u32 v0, v2, 5, 1
	s_cmp_ge_i32 s22, s20
	v_lshlrev_b32_e32 v24, 3, v0
	v_lshlrev_b32_e32 v9, 4, v0
	v_lshl_or_b32 v1, s8, 6, v8
	s_cselect_b64 s[8:9], -1, 0
	v_lshl_or_b32 v0, v0, 2, s21
	s_lshl_b32 s33, s20, 6
	s_add_i32 s20, s33, 0
	v_or_b32_e32 v13, 2, v0
	v_or_b32_e32 v15, 3, v0
	v_or_b32_e32 v16, 8, v0
	v_or_b32_e32 v25, 9, v0
	v_or_b32_e32 v26, 10, v0
	v_or_b32_e32 v27, 11, v0
	v_or_b32_e32 v28, 16, v0
	v_or_b32_e32 v29, 17, v0
	v_or_b32_e32 v30, 18, v0
	v_or_b32_e32 v31, 19, v0
	v_or_b32_e32 v32, 24, v0
	v_or_b32_e32 v33, 25, v0
	v_or_b32_e32 v34, 26, v0
	v_or_b32_e32 v35, 27, v0
	v_or_b32_e32 v14, s21, v8
	v_mul_lo_u32 v123, v1, s3
	v_lshl_or_b32 v3, s22, 5, v8
	v_add_u32_e32 v124, s20, v24
	v_lshl_add_u32 v125, v1, 2, s14
	v_cmp_le_i32_e64 s[20:21], v0, v1
	v_cmp_lt_i32_e64 s[22:23], v0, v1
	v_cmp_le_i32_e64 s[24:25], v13, v1
	v_cmp_le_i32_e64 s[26:27], v15, v1
	v_cmp_le_i32_e64 s[28:29], v16, v1
	v_cmp_le_i32_e64 s[30:31], v25, v1
	v_cmp_le_i32_e64 s[34:35], v26, v1
	v_cmp_le_i32_e64 s[36:37], v27, v1
	v_cmp_le_i32_e64 s[38:39], v28, v1
	v_cmp_le_i32_e64 s[40:41], v29, v1
	v_cmp_le_i32_e64 s[42:43], v30, v1
	v_cmp_le_i32_e64 s[44:45], v31, v1
	v_cmp_le_i32_e64 s[46:47], v32, v1
	v_cmp_le_i32_e64 s[48:49], v33, v1
	v_cmp_le_i32_e64 s[50:51], v34, v1
	v_cmp_le_i32_e64 s[52:53], v35, v1
	v_or_b32_e32 v1, 32, v1
	v_lshl_add_u32 v126, v0, 2, s11
	v_lshl_add_u32 v127, v13, 2, s11
	v_lshl_add_u32 v128, v15, 2, s11
	v_lshl_add_u32 v129, v16, 2, s11
	v_lshl_add_u32 v130, v25, 2, s11
	v_lshl_add_u32 v131, v26, 2, s11
	v_lshl_add_u32 v132, v27, 2, s11
	v_lshl_add_u32 v133, v28, 2, s11
	v_lshl_add_u32 v134, v29, 2, s11
	v_lshl_add_u32 v135, v30, 2, s11
	v_lshl_add_u32 v136, v31, 2, s11
	v_lshl_add_u32 v137, v32, 2, s11
	v_lshl_add_u32 v138, v33, 2, s11
	v_lshl_add_u32 v139, v34, 2, s11
	v_lshl_add_u32 v140, v35, 2, s11
	v_cmp_le_i32_e64 s[54:55], v0, v1
	v_cmp_lt_i32_e64 s[56:57], v0, v1
	v_lshrrev_b32_e32 v0, 2, v2
	s_movk_i32 s11, 0x88
	v_mul_lo_u32 v10, v3, s3
	v_lshl_add_u32 v141, v1, 2, s14
	v_mul_lo_u32 v3, v1, s3
	v_cmp_le_i32_e64 s[58:59], v13, v1
	v_cmp_le_i32_e64 s[60:61], v15, v1
	v_cmp_le_i32_e64 s[62:63], v16, v1
	v_cmp_le_i32_e64 s[64:65], v25, v1
	v_cmp_le_i32_e64 s[66:67], v26, v1
	v_cmp_le_i32_e64 s[68:69], v27, v1
	v_cmp_le_i32_e64 s[70:71], v28, v1
	v_cmp_le_i32_e64 s[72:73], v29, v1
	v_cmp_le_i32_e64 s[74:75], v30, v1
	v_cmp_le_i32_e64 s[76:77], v31, v1
	v_cmp_le_i32_e64 s[78:79], v32, v1
	v_cmp_le_i32_e64 s[80:81], v33, v1
	v_cmp_le_i32_e64 s[82:83], v34, v1
	v_cmp_le_i32_e64 s[84:85], v35, v1
	v_and_b32_e32 v1, 3, v2
	v_mul_lo_u32 v0, v0, s11
	v_mbcnt_hi_u32_b32 v15, -1, v193
	v_lshl_add_u32 v0, v1, 5, v0
	v_and_b32_e32 v16, 64, v15
	v_lshl_add_u32 v143, v0, 1, 0
	v_xor_b32_e32 v0, 1, v15
	v_add_u32_e32 v25, 64, v16
	v_cmp_lt_i32_e32 vcc, v0, v25
	v_add_u32_e32 v121, 0, v9
	s_add_i32 s11, 0, 0x23000
	v_cndmask_b32_e32 v0, v15, v0, vcc
	v_lshlrev_b32_e32 v144, 2, v0
	v_xor_b32_e32 v0, 2, v15
	v_lshlrev_b32_e32 v26, 2, v14
	v_mul_u32_u24_e32 v11, 0x110, v14
	v_mad_u32_u24 v122, v14, s3, v121
	v_cmp_lt_i32_e32 vcc, v0, v25
	v_add_u32_e32 v151, s15, v26
	v_add_u32_e32 v175, s11, v26
	v_xor_b32_e32 v26, 32, v15
	v_lshlrev_b32_e32 v177, 3, v14
	v_mul_u32_u24_e32 v14, 0x210, v14
	v_cndmask_b32_e32 v0, v15, v0, vcc
	v_cmp_lt_i32_e32 vcc, v26, v25
	v_add3_u32 v14, 0, v14, v24
	v_add_u32_e32 v24, -1, v15
	v_cndmask_b32_e32 v25, v15, v26, vcc
	v_cmp_lt_i32_e32 vcc, v24, v16
	v_lshlrev_b32_e32 v145, 2, v0
	v_and_b32_e32 v0, -4, v2
	s_lshl_b32 s14, s2, 5
	v_cndmask_b32_e32 v24, v24, v15, vcc
	v_add_u32_e32 v147, s18, v0
	s_and_b32 s18, s14, 0xfffff80
	v_lshlrev_b32_e32 v187, 2, v24
	v_add_u32_e32 v24, -2, v15
	v_add_u32_e32 v146, s15, v0
	v_add_u32_e32 v148, s11, v0
	v_or_b32_e32 v0, s18, v8
	v_cmp_lt_i32_e32 vcc, v24, v16
	v_mul_lo_u32 v13, v0, s3
	v_or_b32_e32 v0, s14, v8
	v_cndmask_b32_e32 v24, v24, v15, vcc
	v_or_b32_e32 v0, 0x60, v0
	v_lshlrev_b32_e32 v188, 2, v24
	v_add_u32_e32 v24, -4, v15
	v_mul_lo_u32 v150, v0, s3
	v_and_b32_e32 v0, 1, v2
	v_cmp_lt_i32_e32 vcc, v24, v16
	v_lshl_or_b32 v27, s2, 2, v0
	s_movk_i32 s14, 0x880
	v_cndmask_b32_e32 v24, v24, v15, vcc
	v_lshlrev_b32_e32 v0, 3, v27
	v_mul_lo_u32 v27, v27, s14
	s_and_b32 s14, s10, 0xffffff00
	v_lshlrev_b32_e32 v189, 2, v24
	v_add_u32_e32 v24, -8, v15
	s_lshl_b32 s10, s14, 2
	v_cmp_lt_i32_e32 vcc, v24, v16
	v_writelane_b32 v248, s8, 24
	s_add_i32 s10, s10, 0
	v_cndmask_b32_e32 v24, v24, v15, vcc
	v_writelane_b32 v248, s9, 25
	v_bfe_u32 v152, v2, 1, 5
	s_add_i32 s8, s10, 0x23400
	v_lshlrev_b32_e32 v190, 2, v24
	v_add_u32_e32 v24, -16, v15
	v_and_b32_e32 v28, 62, v2
	v_or_b32_e32 v158, 32, v152
	v_or_b32_e32 v161, 64, v152
	v_or_b32_e32 v164, 0x60, v152
	v_writelane_b32 v248, s8, 28
	s_add_u32 s8, s90, 0x9b80000
	v_cmp_lt_i32_e32 vcc, v24, v16
	v_add_u32_e32 v29, s88, v28
	v_lshlrev_b32_e32 v31, 1, v158
	v_lshlrev_b32_e32 v32, 1, v161
	v_lshlrev_b32_e32 v33, 1, v164
	s_addc_u32 s9, s91, 0
	s_load_dwordx2 s[10:11], s[0:1], 0x70
	v_cndmask_b32_e32 v24, v24, v15, vcc
	s_lshr_b32 s2, s2, 2
	v_lshlrev_b32_e32 v12, 3, v2
	v_add_u32_e32 v153, v29, v27
	v_add_u32_e32 v30, s88, v27
	v_add3_u32 v160, s88, v31, v27
	v_add3_u32 v163, s88, v32, v27
	v_add3_u32 v166, s88, v33, v27
	v_or_b32_e32 v27, 16, v0
	v_lshlrev_b32_e32 v191, 2, v24
	v_subrev_u32_e32 v24, 32, v15
	v_add3_u32 v11, v11, v9, 0
	s_mul_i32 s2, s2, 0x8800
	v_and_b32_e32 v74, 0xffffff80, v12
	v_mul_lo_u32 v27, v27, s3
	s_movk_i32 s15, 0x210
	v_and_b32_e32 v178, 0xf8, v12
	v_ashrrev_i32_e32 v179, 5, v2
	v_ashrrev_i32_e32 v180, 5, v17
	v_ashrrev_i32_e32 v181, 5, v18
	v_ashrrev_i32_e32 v182, 5, v19
	v_ashrrev_i32_e32 v183, 5, v20
	v_ashrrev_i32_e32 v184, 5, v21
	v_ashrrev_i32_e32 v185, 5, v22
	v_ashrrev_i32_e32 v186, 5, v23
	v_cmp_lt_i32_e32 vcc, v24, v16
	v_add_u32_e32 v195, 0x8800, v11
	v_mov_b32_e32 v11, s2
	v_add_u32_e32 v76, 0x1000, v74
	v_add_u32_e32 v78, 0x2000, v74
	v_add_u32_e32 v80, 0x3000, v74
	v_add_u32_e32 v82, 0x4000, v74
	v_add_u32_e32 v84, 0x5000, v74
	v_add_u32_e32 v86, 0x6000, v74
	v_add_u32_e32 v88, 0x7000, v74
	v_add_u32_e32 v120, s88, v68
	v_lshl_add_u32 v142, v1, 7, s19
	v_cmp_eq_u32_e64 s[86:87], 0, v1
	v_add_u32_e32 v149, s88, v9
	v_ashrrev_i32_e32 v1, 31, v0
	v_add_u32_e32 v167, v29, v27
	v_add_u32_e32 v27, s88, v27
	v_lshl_add_u32 v12, v178, 1, 0
	v_mul_lo_u32 v2, v179, s15
	v_mul_lo_u32 v17, v180, s15
	v_mul_lo_u32 v18, v181, s15
	v_mul_lo_u32 v19, v182, s15
	v_mul_lo_u32 v20, v183, s15
	v_mul_lo_u32 v21, v184, s15
	v_mul_lo_u32 v22, v185, s15
	v_mul_lo_u32 v23, v186, s15
	v_cndmask_b32_e32 v15, v24, v15, vcc
	v_mad_u32_u24 v8, v8, s3, v11
	v_ashrrev_i32_e32 v75, 31, v74
	v_ashrrev_i32_e32 v77, 31, v76
	v_ashrrev_i32_e32 v79, 31, v78
	v_ashrrev_i32_e32 v81, 31, v80
	v_ashrrev_i32_e32 v83, 31, v82
	v_ashrrev_i32_e32 v85, 31, v84
	v_ashrrev_i32_e32 v87, 31, v86
	v_ashrrev_i32_e32 v89, 31, v88
	s_mov_b32 s95, 0
	v_add_u32_e32 v154, v30, v28
	v_add_u32_e32 v155, 0x220, v153
	v_add_u32_e32 v156, 0x440, v153
	v_add_u32_e32 v157, 0x660, v153
	v_add_u32_e32 v159, v30, v31
	v_add_u32_e32 v162, v30, v32
	v_add_u32_e32 v165, v30, v33
	v_add_u32_e32 v168, v27, v28
	v_add_u32_e32 v169, 0x1320, v153
	v_add_u32_e32 v170, 0x1540, v153
	v_add_u32_e32 v171, 0x1760, v153
	v_add_u32_e32 v172, v27, v31
	v_add_u32_e32 v173, v27, v32
	v_add_u32_e32 v174, v27, v33
	v_lshlrev_b32_e32 v176, 2, v25
	v_writelane_b32 v248, s8, 26
	v_lshlrev_b32_e32 v194, 2, v15
	s_add_i32 s33, s33, 64
	v_add3_u32 v196, v150, v9, 0
	v_add3_u32 v197, v8, v9, 0
	v_add_u32_e32 v198, v120, v4
	v_add_u32_e32 v199, v120, v5
	v_add_u32_e32 v200, v120, v6
	v_add_u32_e32 v201, v120, v7
	v_add_u32_e32 v202, v121, v10
	v_add_u32_e32 v203, v149, v13
	v_lshlrev_b64 v[92:93], 1, v[0:1]
	v_mov_b32_e32 v204, 0x260
	v_add_u32_e32 v205, s14, v14
	v_add_u32_e32 v206, v12, v2
	v_add_u32_e32 v207, v12, v17
	v_add_u32_e32 v208, v12, v18
	v_add_u32_e32 v209, v12, v19
	v_add_u32_e32 v210, v12, v20
	v_add_u32_e32 v211, v12, v21
	v_add_u32_e32 v212, v12, v22
	v_add_u32_e32 v213, v12, v23
	v_mov_b32_e32 v94, 0x3ecc95a3
	v_mov_b32_e32 v214, 0x7f800000
	v_mov_b32_e32 v215, 0x7fc00000
	v_mov_b32_e32 v216, 0xff800000
	v_add_u32_e32 v217, v124, v3
	s_mov_b32 s2, s96
	v_writelane_b32 v248, s9, 27
	s_branch .LBB0_741

.LBB0_819:
	s_waitcnt vmcnt(0)
	s_barrier
	s_mov_b64 s[2:3], exec
	v_readlane_b32 s4, v248, 7
	v_readlane_b32 s5, v248, 8
	s_and_b64 s[4:5], s[2:3], s[4:5]
	s_mov_b64 exec, s[4:5]
	s_cbranch_execz .LBB0_871
	v_readlane_b32 s4, v248, 4
	v_readlane_b32 s5, v248, 5
	v_readlane_b32 s8, v248, 6
	v_readlane_b32 s9, v249, 14
	v_readlane_b32 s10, v249, 15
	v_mov_b32_e32 v1, 1
	v_mov_b32_e32 v3, 0x3400
	s_nop 1
	s_lshl_b32 s8, s8, 8
	s_mul_i32 s9, s9, 6
	s_mul_i32 s10, s10, 6
	v_mov_b32_e32 v0, s8
	v_add_u32_e32 v2, 0x1000, v0
	v_add_u32_e32 v4, 0x2000, v0
	s_nop 1
	global_atomic_add v5, v2, v1, s[4:5] offset:1024 sc0
	s_waitcnt vmcnt(0)
	v_readfirstlane_b32 s11, v5
	s_nop 1
	s_add_u32 s11, s11, 1
	s_cmp_eq_u32 s11, s9
	s_cbranch_scc0 .Lhb5_follower
	buffer_wbl2 sc1
	s_waitcnt vmcnt(0)
	global_atomic_add v5, v3, v1, s[4:5] sc0
	s_waitcnt vmcnt(0)
	v_readfirstlane_b32 s11, v5
	s_nop 1
	s_add_u32 s11, s11, 1
	s_cmp_ge_u32 s11, s10
	s_cbranch_scc1 .Lhb5_topdone
	s_movk_i32 s12, 0x4000

.Lhb5_fspin:
	global_load_dword v5, v4, s[4:5] offset:1024 sc1
	s_waitcnt vmcnt(0)
	v_readfirstlane_b32 s11, v5
	s_nop 1
	s_cmp_gt_u32 s11, 5
	s_cbranch_scc1 .Lhb5_fdone
	s_sleep 1
	s_sub_u32 s12, s12, 1
	s_cmp_lg_u32 s12, 0
	s_cbranch_scc1 .Lhb5_fspin

.Lhb5_done:
.LBB0_871:
	s_or_b64 exec, exec, s[2:3]
	s_waitcnt lgkmcnt(0)
	v_mov_b32_e32 v0, v192
	s_barrier
	s_load_dwordx2 s[10:11], s[0:1], 0xf0
	v_readlane_b32 s8, v248, 35
	v_readlane_b32 s9, v248, 36
	v_mov_b32_e32 v8, v192
	s_waitcnt lgkmcnt(0)
	s_add_u32 s2, s10, 0xbc80000
	s_addc_u32 s3, s11, 0
	s_add_u32 s4, s10, 0x2800000
	v_cndmask_b32_e64 v0, 0, 1, s[8:9]
	s_addc_u32 s5, s11, 0
	v_cmp_ne_u32_e64 s[6:7], 1, v0
	s_andn2_b64 vcc, exec, s[8:9]
	v_readfirstlane_b32 s18, v8
	s_cbranch_vccnz .LBB0_897
	s_ashr_i32 s33, s96, 31
	s_lshr_b32 s8, s33, 29
	s_add_i32 s13, s96, s8
	s_and_b32 s8, s13, -8
	s_sub_i32 s14, s96, s8
	s_cmp_gt_i32 s14, -1
	s_cbranch_scc0 .LBB0_874
	s_lshl_b32 s12, s14, 5
	s_cbranch_execz .LBB0_875
	s_branch .LBB0_876

.LBB0_904:
	s_waitcnt vmcnt(0)
	s_barrier
	s_mov_b64 s[2:3], exec
	v_readlane_b32 s4, v248, 7
	v_readlane_b32 s5, v248, 8
	s_and_b64 s[4:5], s[2:3], s[4:5]
	s_mov_b64 exec, s[4:5]
	s_cbranch_execz .LBB0_956
	v_readlane_b32 s4, v248, 4
	v_readlane_b32 s5, v248, 5
	v_readlane_b32 s8, v248, 6
	v_readlane_b32 s9, v249, 14
	v_readlane_b32 s10, v249, 15
	v_mov_b32_e32 v1, 1
	v_mov_b32_e32 v3, 0x3400
	s_nop 1
	s_lshl_b32 s8, s8, 8
	s_mul_i32 s9, s9, 7
	s_mul_i32 s10, s10, 7
	v_mov_b32_e32 v0, s8
	v_add_u32_e32 v2, 0x1000, v0
	v_add_u32_e32 v4, 0x2000, v0
	s_nop 1
	global_atomic_add v5, v2, v1, s[4:5] offset:1024 sc0
	s_waitcnt vmcnt(0)
	v_readfirstlane_b32 s11, v5
	s_nop 1
	s_add_u32 s11, s11, 1
	s_cmp_eq_u32 s11, s9
	s_cbranch_scc0 .Lhb6_follower
	buffer_wbl2 sc1
	s_waitcnt vmcnt(0)
	global_atomic_add v5, v3, v1, s[4:5] sc0
	s_waitcnt vmcnt(0)
	v_readfirstlane_b32 s11, v5
	s_nop 1
	s_add_u32 s11, s11, 1
	s_cmp_ge_u32 s11, s10
	s_cbranch_scc1 .Lhb6_topdone
	s_movk_i32 s12, 0x4000

.Lhb6_fspin:
	global_load_dword v5, v4, s[4:5] offset:1024 sc1
	s_waitcnt vmcnt(0)
	v_readfirstlane_b32 s11, v5
	s_nop 1
	s_cmp_gt_u32 s11, 6
	s_cbranch_scc1 .Lhb6_fdone
	s_sleep 1
	s_sub_u32 s12, s12, 1
	s_cmp_lg_u32 s12, 0
	s_cbranch_scc1 .Lhb6_fspin

.Lhb6_done:
.LBB0_956:
	s_or_b64 exec, exec, s[2:3]
	s_waitcnt lgkmcnt(0)
	v_mov_b32_e32 v0, v192
	s_barrier
	s_load_dwordx2 s[4:5], s[0:1], 0xf0
	v_mov_b32_e32 v8, v192
	s_and_b64 vcc, exec, s[6:7]
	v_readfirstlane_b32 s8, v8
	s_cbranch_vccnz .LBB0_962
	s_ashr_i32 s2, s96, 31
	s_lshr_b32 s2, s2, 29
	s_add_i32 s9, s96, s2
	s_and_b32 s2, s9, -8
	s_sub_i32 s10, s96, s2
	s_cmp_gt_i32 s10, -1
	s_cbranch_scc0 .LBB0_959
	s_lshl_b32 s11, s10, 5
	s_cbranch_execz .LBB0_960
	s_branch .LBB0_961

.LBB0_1019:
	s_waitcnt vmcnt(0)
	s_barrier
	s_mov_b64 s[2:3], exec
	v_readlane_b32 s4, v248, 7
	v_readlane_b32 s5, v248, 8
	s_and_b64 s[4:5], s[2:3], s[4:5]
	s_mov_b64 exec, s[4:5]
	s_cbranch_execz .LBB0_1071
	v_readlane_b32 s4, v248, 4
	v_readlane_b32 s5, v248, 5
	v_readlane_b32 s8, v248, 6
	v_readlane_b32 s9, v249, 14
	v_readlane_b32 s10, v249, 15
	v_mov_b32_e32 v1, 1
	v_mov_b32_e32 v3, 0x3400
	s_nop 1
	s_lshl_b32 s8, s8, 8
	s_mul_i32 s9, s9, 8
	s_mul_i32 s10, s10, 8
	v_mov_b32_e32 v0, s8
	v_add_u32_e32 v2, 0x1000, v0
	v_add_u32_e32 v4, 0x2000, v0
	s_nop 1
	global_atomic_add v5, v2, v1, s[4:5] offset:1024 sc0
	s_waitcnt vmcnt(0)
	v_readfirstlane_b32 s11, v5
	s_nop 1
	s_add_u32 s11, s11, 1
	s_cmp_eq_u32 s11, s9
	s_cbranch_scc0 .Lhb7_follower
	buffer_wbl2 sc1
	s_waitcnt vmcnt(0)
	global_atomic_add v5, v3, v1, s[4:5] sc0
	s_waitcnt vmcnt(0)
	v_readfirstlane_b32 s11, v5
	s_nop 1
	s_add_u32 s11, s11, 1
	s_cmp_ge_u32 s11, s10
	s_cbranch_scc1 .Lhb7_topdone
	s_movk_i32 s12, 0x4000

.Lhb7_fspin:
	global_load_dword v5, v4, s[4:5] offset:1024 sc1
	s_waitcnt vmcnt(0)
	v_readfirstlane_b32 s11, v5
	s_nop 1
	s_cmp_gt_u32 s11, 7
	s_cbranch_scc1 .Lhb7_fdone
	s_sleep 1
	s_sub_u32 s12, s12, 1
	s_cmp_lg_u32 s12, 0
	s_cbranch_scc1 .Lhb7_fspin

.Lhb7_done:
.LBB0_1071:
	s_or_b64 exec, exec, s[2:3]
	v_mov_b32_e32 v32, v192
	s_waitcnt lgkmcnt(0)
	s_barrier
	s_nop 0
	v_readfirstlane_b32 s2, v32
	s_ashr_i32 s10, s2, 6
	s_mul_i32 s15, s10, s92
	s_add_i32 s2, s15, s96
	s_cmpk_gt_i32 s2, 0x41ff
	s_cbranch_scc1 .LBB0_1079
	s_load_dwordx2 s[8:9], s[0:1], 0xf0
	s_load_dwordx4 s[20:23], s[0:1], 0x98
	v_lshlrev_b32_e32 v0, 2, v32
	v_and_b32_e32 v34, 0xfc, v0
	v_mov_b32_e32 v65, 0
	s_waitcnt lgkmcnt(0)
	s_add_u32 s16, s8, 0x2380000
	s_addc_u32 s17, s9, 0
	s_ashr_i32 s3, s2, 31
	s_lshl_b64 s[2:3], s[2:3], 11
	s_add_u32 s2, s8, s2
	v_lshlrev_b32_e32 v64, 1, v34
	s_addc_u32 s3, s9, s3
	v_lshl_add_u64 v[36:37], s[2:3], 0, v[64:65]
	s_mov_b64 s[4:5], 0x4900000
	v_lshlrev_b32_e32 v33, 2, v34
	v_lshl_add_u64 v[38:39], v[36:37], 0, s[4:5]
	s_mov_b32 s4, 0x4900000
	global_load_dwordx4 v[0:3], v33, s[20:21] offset:3072
	global_load_dwordx4 v[4:7], v33, s[22:23] offset:3072
	global_load_dwordx4 v[8:11], v33, s[22:23] offset:2048
	global_load_dwordx4 v[12:15], v33, s[20:21] offset:2048
	global_load_dwordx4 v[16:19], v33, s[22:23] offset:1024
	global_load_dwordx4 v[20:23], v33, s[20:21] offset:1024
	global_load_dwordx4 v[24:27], v33, s[22:23]
	global_load_dwordx4 v[28:31], v33, s[20:21]
	v_add_co_u32_e32 v36, vcc, s4, v36
	v_mbcnt_hi_u32_b32 v33, -1, v193
	s_nop 0
	v_addc_co_u32_e32 v37, vcc, 0, v37, vcc
	global_load_dwordx2 v[82:83], v[36:37], off
	global_load_dwordx2 v[80:81], v[38:39], off offset:512
	global_load_dwordx2 v[78:79], v[38:39], off offset:1024
	global_load_dwordx2 v[76:77], v[38:39], off offset:1536
	v_and_b32_e32 v35, 64, v33
	v_add_u32_e32 v35, 64, v35
	v_xor_b32_e32 v36, 1, v33
	v_cmp_lt_i32_e32 vcc, v36, v35
	s_add_i32 s10, s10, 8
	v_readlane_b32 s4, v248, 9
	v_cndmask_b32_e32 v36, v33, v36, vcc
	v_lshlrev_b32_e32 v84, 2, v36
	v_xor_b32_e32 v36, 2, v33
	v_cmp_lt_i32_e32 vcc, v36, v35
	s_mul_i32 s18, s92, s10
	v_readlane_b32 s5, v248, 10
	v_cndmask_b32_e32 v36, v33, v36, vcc
	v_lshlrev_b32_e32 v85, 2, v36
	v_xor_b32_e32 v36, 4, v33
	v_cmp_lt_i32_e32 vcc, v36, v35
	s_add_i32 s10, s96, s18
	s_mov_b32 s12, s4
	v_cndmask_b32_e32 v36, v33, v36, vcc
	v_lshlrev_b32_e32 v86, 2, v36
	v_xor_b32_e32 v36, 8, v33
	v_cmp_lt_i32_e32 vcc, v36, v35
	s_ashr_i32 s13, s4, 31
	v_writelane_b32 v248, s4, 9
	v_cndmask_b32_e32 v36, v33, v36, vcc
	v_lshlrev_b32_e32 v87, 2, v36
	v_xor_b32_e32 v36, 16, v33
	v_cmp_lt_i32_e32 vcc, v36, v35
	s_ashr_i32 s11, s10, 31
	v_writelane_b32 v248, s5, 10
	v_cndmask_b32_e32 v36, v33, v36, vcc
	v_lshlrev_b32_e32 v88, 2, v36
	v_xor_b32_e32 v36, 32, v33
	v_cmp_lt_i32_e32 vcc, v36, v35
	s_lshl_b64 s[4:5], s[12:13], 11
	s_lshl_b64 s[10:11], s[10:11], 11
	v_cndmask_b32_e32 v33, v33, v36, vcc
	v_and_b32_e32 v32, 63, v32
	s_add_u32 s8, s8, s10
	s_mov_b32 s24, -1
	v_lshlrev_b32_e32 v89, 2, v33
	v_lshlrev_b32_e32 v66, 3, v32
	v_mov_b32_e32 v67, v65
	s_addc_u32 s9, s9, s11
	s_movk_i32 s19, 0x4000
	v_lshlrev_b32_e32 v64, 2, v34
	s_mov_b64 s[10:11], 0x3000
	s_mov_b64 s[12:13], 0x4000
	s_mov_b32 s14, 0x3a800000
	s_mov_b32 s20, 0x800000
	s_mov_b32 s21, 0xc800000
	s_mov_b32 s22, 0x2800000
	s_mov_b32 s23, s96
	s_branch .LBB0_1075

.LBB0_1079:
	s_waitcnt vmcnt(0)
	s_barrier
	s_mov_b64 s[2:3], exec
	v_readlane_b32 s4, v248, 7
	v_readlane_b32 s5, v248, 8
	s_and_b64 s[4:5], s[2:3], s[4:5]
	s_mov_b64 exec, s[4:5]
	s_cbranch_execz .LBB0_1131
	v_readlane_b32 s4, v248, 4
	v_readlane_b32 s5, v248, 5
	v_readlane_b32 s8, v248, 6
	v_readlane_b32 s9, v249, 14
	v_readlane_b32 s10, v249, 15
	v_mov_b32_e32 v1, 1
	v_mov_b32_e32 v3, 0x3400
	s_nop 1
	s_lshl_b32 s8, s8, 8
	s_mul_i32 s9, s9, 9
	s_mul_i32 s10, s10, 9
	v_mov_b32_e32 v0, s8
	v_add_u32_e32 v2, 0x1000, v0
	v_add_u32_e32 v4, 0x2000, v0
	s_nop 1
	global_atomic_add v5, v2, v1, s[4:5] offset:1024 sc0
	s_waitcnt vmcnt(0)
	v_readfirstlane_b32 s11, v5
	s_nop 1
	s_add_u32 s11, s11, 1
	s_cmp_eq_u32 s11, s9
	s_cbranch_scc0 .Lhb8_follower
	buffer_wbl2 sc1
	s_waitcnt vmcnt(0)
	global_atomic_add v5, v3, v1, s[4:5] sc0
	s_waitcnt vmcnt(0)
	v_readfirstlane_b32 s11, v5
	s_nop 1
	s_add_u32 s11, s11, 1
	s_cmp_ge_u32 s11, s10
	s_cbranch_scc1 .Lhb8_topdone
	s_movk_i32 s12, 0x4000

.Lhb8_fspin:
	global_load_dword v5, v4, s[4:5] offset:1024 sc1
	s_waitcnt vmcnt(0)
	v_readfirstlane_b32 s11, v5
	s_nop 1
	s_cmp_gt_u32 s11, 8
	s_cbranch_scc1 .Lhb8_fdone
	s_sleep 1
	s_sub_u32 s12, s12, 1
	s_cmp_lg_u32 s12, 0
	s_cbranch_scc1 .Lhb8_fspin

.Lhb8_done:
.LBB0_1131:
	s_or_b64 exec, exec, s[2:3]
	s_waitcnt lgkmcnt(0)
	s_barrier
	v_mov_b32_e32 v0, v192
	s_load_dwordx2 s[4:5], s[0:1], 0xc0
	s_load_dwordx4 s[16:19], s[0:1], 0xb0
	v_mov_b32_e32 v8, v192
	s_cmpk_lt_i32 s96, 0x5ac
	s_cselect_b64 s[8:9], -1, 0
	s_cmpk_gt_i32 s96, 0x5ab
	v_readfirstlane_b32 s28, v8
	s_cbranch_scc1 .LBB0_1137
	s_ashr_i32 s2, s96, 31
	s_lshr_b32 s2, s2, 29
	s_add_i32 s10, s96, s2
	s_and_b32 s2, s10, -8
	s_sub_i32 s11, s96, s2
	s_cmp_gt_i32 s11, 3
	s_cbranch_scc0 .LBB0_1134
	s_mul_i32 s2, s11, 0xb5
	s_add_i32 s12, s2, 4
	s_cbranch_execz .LBB0_1135
	s_branch .LBB0_1136

.LBB0_1214:
	s_waitcnt vmcnt(0)
	s_barrier
	s_mov_b64 s[2:3], exec
	v_readlane_b32 s4, v248, 7
	v_readlane_b32 s5, v248, 8
	s_and_b64 s[4:5], s[2:3], s[4:5]
	s_mov_b64 exec, s[4:5]
	s_cbranch_execz .LBB0_1266
	v_readlane_b32 s4, v248, 4
	v_readlane_b32 s5, v248, 5
	v_readlane_b32 s8, v248, 6
	v_readlane_b32 s9, v249, 14
	v_readlane_b32 s10, v249, 15
	v_mov_b32_e32 v1, 1
	v_mov_b32_e32 v3, 0x3400
	s_nop 1
	s_lshl_b32 s8, s8, 8
	s_mul_i32 s9, s9, 10
	s_mul_i32 s10, s10, 10
	v_mov_b32_e32 v0, s8
	v_add_u32_e32 v2, 0x1000, v0
	v_add_u32_e32 v4, 0x2000, v0
	s_nop 1
	global_atomic_add v5, v2, v1, s[4:5] offset:1024 sc0
	s_waitcnt vmcnt(0)
	v_readfirstlane_b32 s11, v5
	s_nop 1
	s_add_u32 s11, s11, 1
	s_cmp_eq_u32 s11, s9
	s_cbranch_scc0 .Lhb9_follower
	buffer_wbl2 sc1
	s_waitcnt vmcnt(0)
	global_atomic_add v5, v3, v1, s[4:5] sc0
	s_waitcnt vmcnt(0)
	v_readfirstlane_b32 s11, v5
	s_nop 1
	s_add_u32 s11, s11, 1
	s_cmp_ge_u32 s11, s10
	s_cbranch_scc1 .Lhb9_topdone
	s_movk_i32 s12, 0x4000

.Lhb9_fspin:
	global_load_dword v5, v4, s[4:5] offset:1024 sc1
	s_waitcnt vmcnt(0)
	v_readfirstlane_b32 s11, v5
	s_nop 1
	s_cmp_gt_u32 s11, 9
	s_cbranch_scc1 .Lhb9_fdone
	s_sleep 1
	s_sub_u32 s12, s12, 1
	s_cmp_lg_u32 s12, 0
	s_cbranch_scc1 .Lhb9_fspin

.Lhb9_done:
.LBB0_1266:
	s_or_b64 exec, exec, s[2:3]
	s_waitcnt lgkmcnt(0)
	v_mov_b32_e32 v0, v192
	s_barrier
	s_load_dwordx2 s[2:3], s[0:1], 0xf0
	s_and_b64 vcc, exec, s[6:7]
	s_cbranch_vccnz .LBB0_1279
	s_lshr_b32 s4, s97, 29
	s_add_i32 s8, s96, s4
	s_and_b32 s4, s8, -8
	s_sub_i32 s9, s96, s4
	s_cmp_gt_i32 s9, -1
	s_cbranch_scc0 .LBB0_1269
	s_lshl_b32 s10, s9, 5
	s_cbranch_execz .LBB0_1270
	s_branch .LBB0_1271

.LBB0_1349:
	s_waitcnt vmcnt(0)
	s_waitcnt lgkmcnt(0)
	s_barrier
	s_mov_b64 s[2:3], exec
	v_readlane_b32 s4, v248, 7
	v_readlane_b32 s5, v248, 8
	s_and_b64 s[4:5], s[2:3], s[4:5]
	s_mov_b64 exec, s[4:5]
	s_cbranch_execz .LBB0_1401
	v_readlane_b32 s4, v248, 4
	v_readlane_b32 s5, v248, 5
	v_readlane_b32 s8, v248, 6
	v_readlane_b32 s9, v249, 14
	v_readlane_b32 s10, v249, 15
	v_mov_b32_e32 v1, 1
	v_mov_b32_e32 v3, 0x3400
	s_nop 1
	s_lshl_b32 s8, s8, 8
	s_mul_i32 s9, s9, 11
	s_mul_i32 s10, s10, 11
	v_mov_b32_e32 v0, s8
	v_add_u32_e32 v2, 0x1000, v0
	v_add_u32_e32 v4, 0x2000, v0
	s_nop 1
	global_atomic_add v5, v2, v1, s[4:5] offset:1024 sc0
	s_waitcnt vmcnt(0)
	v_readfirstlane_b32 s11, v5
	s_nop 1
	s_add_u32 s11, s11, 1
	s_cmp_eq_u32 s11, s9
	s_cbranch_scc0 .Lhb10_follower
	buffer_wbl2 sc1
	s_waitcnt vmcnt(0)
	global_atomic_add v5, v3, v1, s[4:5] sc0
	s_waitcnt vmcnt(0)
	v_readfirstlane_b32 s11, v5
	s_nop 1
	s_add_u32 s11, s11, 1
	s_cmp_ge_u32 s11, s10
	s_cbranch_scc1 .Lhb10_topdone
	s_movk_i32 s12, 0x4000

.Lhb10_fspin:
	global_load_dword v5, v4, s[4:5] offset:1024 sc1
	s_waitcnt vmcnt(0)
	v_readfirstlane_b32 s11, v5
	s_nop 1
	s_cmp_gt_u32 s11, 10
	s_cbranch_scc1 .Lhb10_fdone
	s_sleep 1
	s_sub_u32 s12, s12, 1
	s_cmp_lg_u32 s12, 0
	s_cbranch_scc1 .Lhb10_fspin

.Lhb10_done:
.LBB0_1401:
	s_or_b64 exec, exec, s[2:3]
	s_waitcnt lgkmcnt(0)
	s_barrier
	s_nop 0
	v_readfirstlane_b32 s2, v192
	s_ashr_i32 s2, s2, 6
	s_mul_i32 s2, s2, s92
	s_add_i32 s2, s2, s96
	s_cmpk_gt_i32 s2, 0x1ff
	s_cbranch_scc1 .LBB0_1404
	v_mbcnt_hi_u32_b32 v0, -1, v193
	v_and_b32_e32 v1, 64, v0
	v_add_u32_e32 v1, 64, v1
	v_xor_b32_e32 v2, 1, v0
	v_cmp_lt_i32_e32 vcc, v2, v1
	s_load_dwordx4 s[4:7], s[0:1], 0xd8
	s_load_dwordx2 s[8:9], s[0:1], 0xe8
	v_cndmask_b32_e32 v2, v0, v2, vcc
	s_waitcnt vmcnt(2)
	v_lshlrev_b32_e32 v12, 2, v2
	v_xor_b32_e32 v2, 2, v0
	v_cmp_lt_i32_e32 vcc, v2, v1
	s_addk_i32 s2, 0x4000
	v_mov_b32_e32 v5, 0
	v_cndmask_b32_e32 v2, v0, v2, vcc
	v_lshlrev_b32_e32 v13, 2, v2
	v_xor_b32_e32 v2, 4, v0
	v_cmp_lt_i32_e32 vcc, v2, v1
	s_ashr_i32 s3, s2, 31
	s_nop 0
	v_cndmask_b32_e32 v2, v0, v2, vcc
	s_waitcnt vmcnt(1)
	v_lshlrev_b32_e32 v14, 2, v2
	v_xor_b32_e32 v2, 8, v0
	v_cmp_lt_i32_e32 vcc, v2, v1
	s_nop 1
	v_cndmask_b32_e32 v2, v0, v2, vcc
	v_lshlrev_b32_e32 v15, 2, v2
	v_xor_b32_e32 v2, 16, v0
	v_cmp_lt_i32_e32 vcc, v2, v1
	s_nop 1
	v_cndmask_b32_e32 v2, v0, v2, vcc
	s_waitcnt vmcnt(0)
	v_lshlrev_b32_e32 v16, 2, v2
	v_xor_b32_e32 v2, 32, v0
	v_cmp_lt_i32_e32 vcc, v2, v1
	s_nop 1
	v_cndmask_b32_e32 v0, v0, v2, vcc
	v_lshlrev_b32_e32 v17, 2, v0
	v_lshlrev_b32_e32 v0, 4, v192
	v_and_b32_e32 v4, 0x3f0, v0
	s_waitcnt lgkmcnt(0)
	v_lshl_add_u64 v[6:7], s[4:5], 0, v[4:5]
	s_lshl_b64 s[4:5], s[2:3], 12
	s_add_u32 s4, s8, s4
	v_and_b32_e32 v0, 63, v192
	s_addc_u32 s5, s9, s5
	v_readlane_b32 s8, v248, 9
	v_lshl_add_u64 v[8:9], s[6:7], 0, v[4:5]
	v_lshlrev_b32_e32 v4, 4, v0
	v_readlane_b32 s9, v248, 10
	v_lshl_add_u64 v[0:1], s[4:5], 0, v[4:5]
	s_mov_b64 s[4:5], 0xc00
	s_ashr_i32 s9, s8, 31
	v_lshl_add_u64 v[10:11], v[0:1], 0, s[4:5]
	s_lshl_b64 s[4:5], s[8:9], 12
	s_mov_b32 s6, 0x3a800000
	s_mov_b32 s3, 0x800000
